# dprep stage A: guarded head-row loads batched; first-section row loads all in flight
# speedup vs baseline: 1.0080x; 1.0080x over previous
; #define LAS __attribute__((address_space(3)))
; DI const float* INP(const Args& a, int i) { asm volatile("" : "+s"(i)); return a.in[i]; }
; DI float bflo(unsigned w) { return __uint_as_float(w << 16); }
; DI float bfhi(unsigned w) { return __uint_as_float(w & 0xffff0000u); }
; DI void dprep_item(LAS unsigned char* ldsh, const Args& a, int l, int item, int tl) {
;     ...
;     { const int cg4 = tl & 31, rg = tl >> 5, c0 = cg4 * 4;
;       for (int sec = 0; sec < 3; ++sec) {
;           const int col = sec * 512 + h * 128 + c0;
;           f32x4 w[4];
; #pragma unroll
;           for (int i = 0; i < 4; ++i) w[i] = *(const f32x4*)(INP(a, 11) + (size_t)(l * 4 + i) * QKVD + col);
;           f32x4 xin[11];
; #pragma unroll
;           for (int i = 0; i < 11; ++i) { const int tpos = n * 64 + rg * 8 - 3 + i;
;               if (tpos >= 0) { const u32x2 raw = *(const u32x2*)(PROJ + (size_t)(r0 + rg * 8 - 3 + i) * NPROJ + col); xin[i] = (f32x4){bflo(raw.x), bfhi(raw.x), bflo(raw.y), bfhi(raw.y)}; }
;               else xin[i] = (f32x4){0.f, 0.f, 0.f, 0.f}; }
;           LAS bf16_t* dst = sec == 0 ? qn : (sec == 1 ? kn : vv);
; #pragma unroll
;           for (int j = 0; j < 8; ++j) { f32x4 o = w[0] * xin[j] + w[1] * xin[j + 1] + w[2] * xin[j + 2] + w[3] * xin[j + 3];
.LBB0_223:
	v_mov_b32_e32 v80, v152
	s_mov_b32 s8, 11
	s_ashr_i32 s9, s8, 31
	s_lshl_b64 s[8:9], s[8:9], 3
	s_add_u32 s8, s0, s8
	s_addc_u32 s9, s1, s9
	s_load_dwordx2 s[8:9], s[8:9], 0x0
	v_ashrrev_i32_e32 v82, 8, v80
	v_lshl_add_u32 v40, s36, 1, v82
	s_waitcnt vmcnt(0)
	v_lshlrev_b32_e32 v0, 2, v80
	v_bfe_u32 v41, v40, 5, 2
	v_and_b32_e32 v86, 0x7c, v0
	v_lshl_or_b32 v84, v41, 7, v86
	s_waitcnt lgkmcnt(0)
	s_add_u32 s8, s8, s2
	s_addc_u32 s9, s9, s14
	v_lshlrev_b32_e32 v12, 2, v84
	global_load_dwordx4 v[0:3], v12, s[8:9]
	s_mov_b32 s8, 11
	s_ashr_i32 s9, s8, 31
	s_lshl_b64 s[8:9], s[8:9], 3
	s_add_u32 s8, s0, s8
	s_addc_u32 s9, s1, s9
	s_load_dwordx2 s[8:9], s[8:9], 0x0
	v_lshlrev_b32_e32 v17, 6, v40
	v_lshlrev_b32_e32 v16, 4, v40
	v_and_b32_e32 v17, 0x7c0, v17
	v_bfe_u32 v81, v80, 2, 6
	s_waitcnt lgkmcnt(0)
	s_add_u32 s8, s8, s16
	s_addc_u32 s9, s9, s15
	global_load_dwordx4 v[4:7], v12, s[8:9]
	s_mov_b32 s8, 11
	s_ashr_i32 s9, s8, 31
	s_lshl_b64 s[8:9], s[8:9], 3
	s_add_u32 s8, s0, s8
	s_addc_u32 s9, s1, s9
	s_load_dwordx2 s[8:9], s[8:9], 0x0
	v_and_b32_e32 v96, 56, v81
	v_lshlrev_b32_e32 v128, 1, v84
	v_lshl_add_u64 v[48:49], s[72:73], 0, v[128:129]
	v_mov_b32_e32 v72, 0
	s_waitcnt lgkmcnt(0)
	s_add_u32 s8, s8, s28
	s_addc_u32 s9, s9, s17
	global_load_dwordx4 v[8:11], v12, s[8:9]
	s_mov_b32 s8, 11
	s_ashr_i32 s9, s8, 31
	s_lshl_b64 s[8:9], s[8:9], 3
	s_add_u32 s8, s0, s8
	s_addc_u32 s9, s1, s9
	s_load_dwordx2 s[8:9], s[8:9], 0x0
	v_mov_b32_e32 v76, 0
	v_mov_b32_e32 v77, 0
	v_mov_b32_e32 v78, 0
	v_mov_b32_e32 v79, 0
	s_waitcnt lgkmcnt(0)
	s_add_u32 s8, s8, s34
	s_addc_u32 s9, s9, s29
	global_load_dwordx4 v[12:15], v12, s[8:9]
	s_movk_i32 s8, 0xf800
	v_and_or_b32 v85, v16, s8, v17
	v_or_b32_e32 v16, v17, v96
	v_or_b32_e32 v20, v96, v85
	v_add_u32_e32 v94, -3, v20
	v_cmp_ne_u32_e64 s[8:9], 0, v16
	v_mov_b32_e32 v180, 0
	v_mov_b32_e32 v181, 0
	s_and_saveexec_b64 s[10:11], s[8:9]
	s_cbranch_execz .LBB0_225
	v_mad_i64_i32 v[16:17], s[12:13], v94, s42, v[48:49]
	global_load_dwordx2 v[180:181], v[16:17], off
.LBB0_225:
	s_or_b64 exec, exec, s[10:11]
	v_add_u32_e32 v95, 1, v94
	v_mov_b32_e32 v73, 0
	v_mov_b32_e32 v74, 0
	v_mov_b32_e32 v75, 0
	v_mov_b32_e32 v182, 0
	v_mov_b32_e32 v183, 0
	s_and_saveexec_b64 s[10:11], s[8:9]
	s_cbranch_execz .LBB0_227
	v_mad_i64_i32 v[16:17], s[12:13], v95, s42, v[48:49]
	global_load_dwordx2 v[182:183], v[16:17], off
.LBB0_227:
	s_or_b64 exec, exec, s[10:11]
	v_or_b32_e32 v16, 2, v94
	v_mad_i64_i32 v[16:17], s[10:11], v16, s42, 0
	v_mov_b32_e32 v68, 0
	v_mov_b32_e32 v69, 0
	v_mov_b32_e32 v70, 0
	v_mov_b32_e32 v71, 0
	v_mov_b32_e32 v184, 0
	v_mov_b32_e32 v185, 0
	s_and_saveexec_b64 s[10:11], s[8:9]
	s_cbranch_execz .LBB0_229
	v_lshl_add_u64 v[18:19], v[48:49], 0, v[16:17]
	global_load_dwordx2 v[184:185], v[18:19], off
.LBB0_229:
	s_or_b64 exec, exec, s[10:11]
	s_waitcnt vmcnt(0)
	v_lshlrev_b32_e32 v76, 16, v180
	v_and_b32_e32 v77, 0xffff0000, v180
	v_lshlrev_b32_e32 v78, 16, v181
	v_and_b32_e32 v79, 0xffff0000, v181
	v_lshlrev_b32_e32 v72, 16, v182
	v_and_b32_e32 v73, 0xffff0000, v182
	v_lshlrev_b32_e32 v74, 16, v183
	v_and_b32_e32 v75, 0xffff0000, v183
	v_lshlrev_b32_e32 v68, 16, v184
	v_and_b32_e32 v69, 0xffff0000, v184
	v_lshlrev_b32_e32 v70, 16, v185
	v_and_b32_e32 v71, 0xffff0000, v185
	v_mad_i64_i32 v[18:19], s[10:11], v20, s42, 0
	v_mad_i64_i32 v[20:21], s[10:11], v20, s42, v[48:49]
	global_load_dwordx2 v[20:21], v[20:21], off
	v_add_u32_e32 v22, 4, v94
	v_add_u32_e32 v24, 5, v94
	v_add_u32_e32 v26, 6, v94
	v_add_u32_e32 v28, 7, v94
	v_add_u32_e32 v30, 8, v94
	v_add_u32_e32 v32, 9, v94
	v_add_u32_e32 v200, 10, v94
	v_mad_i64_i32 v[186:187], s[10:11], v22, s42, v[48:49]
	global_load_dwordx2 v[186:187], v[186:187], off
	v_mad_i64_i32 v[188:189], s[10:11], v24, s42, v[48:49]
	global_load_dwordx2 v[188:189], v[188:189], off
	v_mad_i64_i32 v[190:191], s[10:11], v26, s42, v[48:49]
	global_load_dwordx2 v[190:191], v[190:191], off
	v_mad_i64_i32 v[192:193], s[10:11], v28, s42, v[48:49]
	global_load_dwordx2 v[192:193], v[192:193], off
	v_mad_i64_i32 v[194:195], s[10:11], v30, s42, v[48:49]
	global_load_dwordx2 v[194:195], v[194:195], off
	v_mad_i64_i32 v[196:197], s[10:11], v32, s42, v[48:49]
	global_load_dwordx2 v[196:197], v[196:197], off
	v_mad_i64_i32 v[198:199], s[10:11], v200, s42, v[48:49]
	global_load_dwordx2 v[198:199], v[198:199], off
	v_pk_mul_f32 v[90:91], v[4:5], v[72:73]
	v_pk_mul_f32 v[102:103], v[4:5], v[68:69]
	v_pk_fma_f32 v[76:77], v[0:1], v[76:77], v[90:91]
	v_pk_fma_f32 v[72:73], v[0:1], v[72:73], v[102:103]
	v_pk_fma_f32 v[76:77], v[8:9], v[68:69], v[76:77]
	v_pk_mul_f32 v[88:89], v[6:7], v[74:75]
	v_pk_mul_f32 v[100:101], v[6:7], v[70:71]
	v_pk_fma_f32 v[78:79], v[2:3], v[78:79], v[88:89]
	v_pk_fma_f32 v[74:75], v[2:3], v[74:75], v[100:101]
	v_pk_fma_f32 v[78:79], v[10:11], v[70:71], v[78:79]
	v_xor_b32_e32 v93, 1, v160
	v_add_u32_e32 v54, 10, v94
	s_mov_b32 s12, 0x358637bd
	v_mad_i32_i24 v131, v82, s51, 0
	v_lshl_add_u32 v86, v86, 1, v131
	v_mul_i32_i24_e32 v83, 0x11000, v82
	s_movk_i32 s38, 0x200
	s_movk_i32 s37, 0x4400
	s_waitcnt vmcnt(7)
	v_lshlrev_b32_e32 v64, 16, v20
	v_and_b32_e32 v65, 0xffff0000, v20
	v_lshlrev_b32_e32 v66, 16, v21
	v_and_b32_e32 v67, 0xffff0000, v21
	v_mad_i64_i32 v[20:21], s[10:11], v22, s42, 0
	v_pk_fma_f32 v[76:77], v[12:13], v[64:65], v[76:77]
	v_pk_fma_f32 v[72:73], v[8:9], v[64:65], v[72:73]
	v_mul_f32_e32 v87, 0xbfb8aa3b, v76
	v_exp_f32_e32 v87, v87
	v_pk_fma_f32 v[78:79], v[14:15], v[66:67], v[78:79]
	v_pk_fma_f32 v[74:75], v[10:11], v[66:67], v[74:75]
	v_add_f32_e32 v87, 1.0, v87
	v_rcp_f32_e32 v88, v87
	v_mul_f32_e32 v87, 0xbfb8aa3b, v77
	v_exp_f32_e32 v87, v87
	s_waitcnt vmcnt(6)
; #define LAS __attribute__((address_space(3)))
; DI unsigned pk2(float a, float b) { f32x2 v = {a, b}; nbf2 r = __builtin_convertvector(v, nbf2); return __builtin_bit_cast(unsigned, r); }
; DI float bflo(unsigned w) { return __uint_as_float(w << 16); }
; DI float bfhi(unsigned w) { return __uint_as_float(w & 0xffff0000u); }
; DI float silu_f(float x) { return x * __builtin_amdgcn_rcpf(1.f + __expf(-x)); }
; DI void dprep_item(LAS unsigned char* ldsh, const Args& a, int l, int item, int tl) {
;     ...
;           for (int i = 0; i < 11; ++i) { const int tpos = n * 64 + rg * 8 - 3 + i;
;               if (tpos >= 0) { const u32x2 raw = *(const u32x2*)(PROJ + (size_t)(r0 + rg * 8 - 3 + i) * NPROJ + col); xin[i] = (f32x4){bflo(raw.x), bfhi(raw.x), bflo(raw.y), bfhi(raw.y)}; }
;               else xin[i] = (f32x4){0.f, 0.f, 0.f, 0.f}; }
;           LAS bf16_t* dst = sec == 0 ? qn : (sec == 1 ? kn : vv);
; #pragma unroll
;           for (int j = 0; j < 8; ++j) { f32x4 o = w[0] * xin[j] + w[1] * xin[j + 1] + w[2] * xin[j + 2] + w[3] * xin[j + 3];
;               o[0] = silu_f(o[0]); o[1] = silu_f(o[1]); o[2] = silu_f(o[2]); o[3] = silu_f(o[3]);
;               if (sec < 2) { float ss = (o[0] * o[0] + o[1] * o[1]) + (o[2] * o[2] + o[3] * o[3]);
;                   ss += __shfl_xor(ss, 16); ss += __shfl_xor(ss, 8); ss += __shfl_xor(ss, 4); ss += __shfl_xor(ss, 2); ss += __shfl_xor(ss, 1);
;                   const float sc = rsqrtf(ss + 1e-6f) * (sec == 0 ? 0.08838834764831845f : 1.f); o = o * sc; }
;               u32x2 pw; pw.x = pk2(o[0], o[1]); pw.y = pk2(o[2], o[3]); *(LAS u32x2*)(dst + (rg * 8 + j) * 136 + c0) = pw; }
	v_lshlrev_b32_e32 v60, 16, v186
	v_and_b32_e32 v61, 0xffff0000, v186
	v_lshlrev_b32_e32 v62, 16, v187
	v_and_b32_e32 v63, 0xffff0000, v187
	v_mad_i64_i32 v[22:23], s[10:11], v24, s42, 0
	v_pk_fma_f32 v[72:73], v[12:13], v[60:61], v[72:73]
	v_add_f32_e32 v87, 1.0, v87
	v_mul_f32_e32 v97, 0xbfb8aa3b, v72
	v_exp_f32_e32 v97, v97
	v_rcp_f32_e32 v89, v87
	v_mul_f32_e32 v87, 0xbfb8aa3b, v78
	v_pk_fma_f32 v[74:75], v[14:15], v[62:63], v[74:75]
	v_add_f32_e32 v97, 1.0, v97
	v_rcp_f32_e32 v100, v97
	v_mul_f32_e32 v97, 0xbfb8aa3b, v73
	v_exp_f32_e32 v97, v97
	v_exp_f32_e32 v87, v87
	v_pk_mul_f32 v[76:77], v[76:77], v[88:89]
	v_add_f32_e32 v97, 1.0, v97
	v_rcp_f32_e32 v101, v97
	v_mul_f32_e32 v97, 0xbfb8aa3b, v74
	v_exp_f32_e32 v97, v97
	v_add_f32_e32 v87, 1.0, v87
	v_rcp_f32_e32 v88, v87
	v_mul_f32_e32 v87, 0xbfb8aa3b, v79
	v_add_f32_e32 v97, 1.0, v97
	v_exp_f32_e32 v87, v87
	v_pk_mul_f32 v[72:73], v[72:73], v[100:101]
	v_rcp_f32_e32 v100, v97
	v_mul_f32_e32 v97, 0xbfb8aa3b, v75
	v_exp_f32_e32 v97, v97
	v_add_f32_e32 v87, 1.0, v87
	v_rcp_f32_e32 v89, v87
	v_mov_b32_e32 v90, v77
	v_add_f32_e32 v97, 1.0, v97
	v_rcp_f32_e32 v101, v97
	v_pk_mul_f32 v[78:79], v[78:79], v[88:89]
	v_mov_b32_e32 v88, v76
	v_mov_b32_e32 v91, v79
	v_pk_mul_f32 v[74:75], v[74:75], v[100:101]
	v_mov_b32_e32 v89, v78
	v_pk_mul_f32 v[90:91], v[90:91], v[90:91]
	v_and_b32_e32 v87, 64, v160
	v_mov_b32_e32 v102, v73
	v_mov_b32_e32 v103, v75
	v_pk_fma_f32 v[98:99], v[88:89], v[88:89], v[90:91]
	v_xor_b32_e32 v88, 16, v160
	v_add_u32_e32 v92, 64, v87
	v_mov_b32_e32 v100, v72
	v_mov_b32_e32 v101, v74
	v_pk_mul_f32 v[102:103], v[102:103], v[102:103]
	v_cmp_lt_i32_e32 vcc, v88, v92
	v_pk_fma_f32 v[100:101], v[100:101], v[100:101], v[102:103]
	v_mov_b32_e32 v103, v98
	v_cndmask_b32_e32 v88, v160, v88, vcc
	v_mov_b32_e32 v102, v100
	v_mov_b32_e32 v98, v101
	v_lshlrev_b32_e32 v88, 2, v88
	v_pk_add_f32 v[98:99], v[102:103], v[98:99]
	ds_bpermute_b32 v101, v88, v99
	ds_bpermute_b32 v100, v88, v98
	v_xor_b32_e32 v89, 8, v160
	v_cmp_lt_i32_e32 vcc, v89, v92
	v_xor_b32_e32 v90, 4, v160
	v_xor_b32_e32 v91, 2, v160
	v_cndmask_b32_e32 v89, v160, v89, vcc
	v_lshlrev_b32_e32 v89, 2, v89
	s_waitcnt lgkmcnt(0)
	v_pk_add_f32 v[98:99], v[98:99], v[100:101]
	ds_bpermute_b32 v101, v89, v99
	ds_bpermute_b32 v100, v89, v98
	v_cmp_lt_i32_e32 vcc, v90, v92
	s_waitcnt lgkmcnt(0)
	v_pk_add_f32 v[98:99], v[98:99], v[100:101]
	v_cndmask_b32_e32 v90, v160, v90, vcc
	v_lshlrev_b32_e32 v90, 2, v90
	ds_bpermute_b32 v101, v90, v99
	ds_bpermute_b32 v100, v90, v98
	v_cmp_lt_i32_e32 vcc, v91, v92
	s_waitcnt vmcnt(5)
	v_lshlrev_b32_e32 v56, 16, v188
	v_and_b32_e32 v57, 0xffff0000, v188
	v_lshlrev_b32_e32 v58, 16, v189
	v_and_b32_e32 v59, 0xffff0000, v189
	v_mad_i64_i32 v[24:25], s[10:11], v26, s42, 0
	v_cndmask_b32_e32 v91, v160, v91, vcc
	v_lshlrev_b32_e32 v91, 2, v91
	s_waitcnt lgkmcnt(0)
	v_pk_add_f32 v[98:99], v[98:99], v[100:101]
	ds_bpermute_b32 v101, v91, v99
	ds_bpermute_b32 v100, v91, v98
	v_cmp_lt_i32_e32 vcc, v93, v92
	s_waitcnt lgkmcnt(0)
	v_pk_add_f32 v[98:99], v[98:99], v[100:101]
	v_cndmask_b32_e32 v92, v160, v93, vcc
	v_lshlrev_b32_e32 v92, 2, v92
	ds_bpermute_b32 v101, v92, v99
	ds_bpermute_b32 v100, v92, v98
	v_mul_u32_u24_e32 v93, 0x110, v96
	v_mad_u32_u24 v96, v96, s47, v86
	s_waitcnt lgkmcnt(0)
	v_pk_add_f32 v[98:99], v[98:99], v[100:101]
	s_nop 0
	v_pk_add_f32 v[98:99], v[98:99], s[12:13] op_sel_hi:[1,0]
	s_waitcnt vmcnt(4)
	v_lshlrev_b32_e32 v50, 16, v190
	v_and_b32_e32 v51, 0xffff0000, v190
	v_lshlrev_b32_e32 v52, 16, v191
	v_and_b32_e32 v53, 0xffff0000, v191
	v_mad_i64_i32 v[26:27], s[10:11], v28, s42, 0
	v_mul_f32_e32 v97, 0x4b800000, v99
	v_cmp_gt_f32_e32 vcc, s46, v98
	s_waitcnt vmcnt(3)
	v_lshlrev_b32_e32 v34, 16, v192
	v_and_b32_e32 v35, 0xffff0000, v192
	v_lshlrev_b32_e32 v36, 16, v193
	v_and_b32_e32 v37, 0xffff0000, v193
	v_mad_i64_i32 v[28:29], s[10:11], v30, s42, 0
	s_waitcnt vmcnt(2)
	v_lshlrev_b32_e32 v38, 16, v194
	v_and_b32_e32 v39, 0xffff0000, v194
	v_lshlrev_b32_e32 v42, 16, v195
	v_and_b32_e32 v43, 0xffff0000, v195
	v_mad_i64_i32 v[30:31], s[10:11], v32, s42, 0
	s_waitcnt vmcnt(1)
	v_lshlrev_b32_e32 v44, 16, v196
	v_and_b32_e32 v45, 0xffff0000, v196
	v_lshlrev_b32_e32 v46, 16, v197
	v_and_b32_e32 v47, 0xffff0000, v197
	v_mad_i64_i32 v[32:33], s[10:11], v54, s42, 0
	v_cmp_gt_f32_e64 s[10:11], s46, v99
	s_waitcnt vmcnt(0)
; #define LAS __attribute__((address_space(3)))
; DI unsigned pk2(float a, float b) { f32x2 v = {a, b}; nbf2 r = __builtin_convertvector(v, nbf2); return __builtin_bit_cast(unsigned, r); }
; DI float silu_f(float x) { return x * __builtin_amdgcn_rcpf(1.f + __expf(-x)); }
; DI void dprep_item(LAS unsigned char* ldsh, const Args& a, int l, int item, int tl) {
;     ...
;           for (int j = 0; j < 8; ++j) { f32x4 o = w[0] * xin[j] + w[1] * xin[j + 1] + w[2] * xin[j + 2] + w[3] * xin[j + 3];
;               o[0] = silu_f(o[0]); o[1] = silu_f(o[1]); o[2] = silu_f(o[2]); o[3] = silu_f(o[3]);
;               if (sec < 2) { float ss = (o[0] * o[0] + o[1] * o[1]) + (o[2] * o[2] + o[3] * o[3]);
;                   ss += __shfl_xor(ss, 16); ss += __shfl_xor(ss, 8); ss += __shfl_xor(ss, 4); ss += __shfl_xor(ss, 2); ss += __shfl_xor(ss, 1);
;                   const float sc = rsqrtf(ss + 1e-6f) * (sec == 0 ? 0.08838834764831845f : 1.f); o = o * sc; }
;               u32x2 pw; pw.x = pk2(o[0], o[1]); pw.y = pk2(o[2], o[3]); *(LAS u32x2*)(dst + (rg * 8 + j) * 136 + c0) = pw; }
	v_lshlrev_b32_e32 v48, 16, v198
	v_cndmask_b32_e64 v97, v99, v97, s[10:11]
	v_rsq_f32_e32 v97, v97
	v_and_b32_e32 v49, 0xffff0000, v198
	v_lshlrev_b32_e32 v54, 16, v199
	v_and_b32_e32 v55, 0xffff0000, v199
	v_mul_f32_e32 v99, 0x45800000, v97
	v_cndmask_b32_e64 v97, v97, v99, s[10:11]
	v_mul_f32_e32 v100, 0x3db504f3, v97
	v_pk_mul_f32 v[78:79], v[78:79], v[100:101] op_sel_hi:[1,0]
	v_pk_mul_f32 v[76:77], v[76:77], v[100:101] op_sel_hi:[1,0]
	s_nop 0
	v_cvt_pk_bf16_f32 v76, v76, v77
	v_cvt_pk_bf16_f32 v77, v78, v79
	v_mul_f32_e32 v78, 0x4b800000, v98
	v_cndmask_b32_e32 v78, v98, v78, vcc
	v_rsq_f32_e32 v78, v78
	s_nop 0
	v_mul_f32_e32 v79, 0x45800000, v78
	v_cndmask_b32_e32 v78, v78, v79, vcc
	v_mul_f32_e32 v78, 0x3db504f3, v78
	v_pk_mul_f32 v[74:75], v[74:75], v[78:79] op_sel_hi:[1,0]
	v_pk_mul_f32 v[72:73], v[72:73], v[78:79] op_sel_hi:[1,0]
	s_nop 0
	v_cvt_pk_bf16_f32 v72, v72, v73
	v_cvt_pk_bf16_f32 v73, v74, v75
	ds_write2_b64 v96, v[76:77], v[72:73] offset1:34
	v_pk_mul_f32 v[72:73], v[4:5], v[64:65]
	v_pk_mul_f32 v[74:75], v[6:7], v[66:67]
	v_pk_fma_f32 v[68:69], v[0:1], v[68:69], v[72:73]
	v_pk_fma_f32 v[70:71], v[2:3], v[70:71], v[74:75]
	v_pk_fma_f32 v[68:69], v[8:9], v[60:61], v[68:69]
	v_pk_fma_f32 v[70:71], v[10:11], v[62:63], v[70:71]
	v_pk_fma_f32 v[68:69], v[12:13], v[56:57], v[68:69]
	v_pk_fma_f32 v[70:71], v[14:15], v[58:59], v[70:71]
	v_mul_f32_e32 v72, 0xbfb8aa3b, v68
	v_mul_f32_e32 v73, 0xbfb8aa3b, v69
	v_exp_f32_e32 v72, v72
	v_exp_f32_e32 v73, v73
	v_pk_mul_f32 v[76:77], v[6:7], v[62:63]
	v_add_f32_e32 v72, 1.0, v72
	v_add_f32_e32 v73, 1.0, v73
	v_rcp_f32_e32 v72, v72
	v_rcp_f32_e32 v73, v73
	v_pk_fma_f32 v[66:67], v[2:3], v[66:67], v[76:77]
	v_pk_mul_f32 v[68:69], v[68:69], v[72:73]
	v_mul_f32_e32 v72, 0xbfb8aa3b, v70
	v_mul_f32_e32 v73, 0xbfb8aa3b, v71
	v_exp_f32_e32 v72, v72
	v_exp_f32_e32 v73, v73
	v_mov_b32_e32 v74, v69
	v_pk_fma_f32 v[66:67], v[10:11], v[58:59], v[66:67]
	v_add_f32_e32 v72, 1.0, v72
	v_add_f32_e32 v73, 1.0, v73
	v_rcp_f32_e32 v72, v72
	v_rcp_f32_e32 v73, v73
	v_pk_fma_f32 v[66:67], v[14:15], v[52:53], v[66:67]
	v_pk_mul_f32 v[70:71], v[70:71], v[72:73]
	s_nop 0
	v_mov_b32_e32 v75, v71
	v_mov_b32_e32 v72, v68
	v_mov_b32_e32 v73, v70
	v_pk_mul_f32 v[74:75], v[74:75], v[74:75]
	s_nop 0
	v_pk_fma_f32 v[72:73], v[72:73], v[72:73], v[74:75]
	v_pk_mul_f32 v[74:75], v[4:5], v[60:61]
	s_nop 0
	v_pk_fma_f32 v[64:65], v[0:1], v[64:65], v[74:75]
	s_nop 0
	v_pk_fma_f32 v[64:65], v[8:9], v[56:57], v[64:65]
	s_nop 0
	v_pk_fma_f32 v[64:65], v[12:13], v[50:51], v[64:65]
	s_nop 0
	v_mul_f32_e32 v74, 0xbfb8aa3b, v64
	v_mul_f32_e32 v75, 0xbfb8aa3b, v65
	v_exp_f32_e32 v74, v74
	v_exp_f32_e32 v75, v75
	v_add_f32_e32 v74, 1.0, v74
	v_add_f32_e32 v75, 1.0, v75
	v_rcp_f32_e32 v74, v74
	v_rcp_f32_e32 v75, v75
	s_nop 0
	v_pk_mul_f32 v[64:65], v[64:65], v[74:75]
	v_mul_f32_e32 v74, 0xbfb8aa3b, v66
	v_mul_f32_e32 v75, 0xbfb8aa3b, v67
	v_exp_f32_e32 v74, v74
	v_exp_f32_e32 v75, v75
	v_mov_b32_e32 v76, v65
	v_add_f32_e32 v74, 1.0, v74
	v_add_f32_e32 v75, 1.0, v75
	v_rcp_f32_e32 v74, v74
	v_rcp_f32_e32 v75, v75
	s_nop 0
	v_pk_mul_f32 v[66:67], v[66:67], v[74:75]
	s_nop 0
	v_mov_b32_e32 v77, v67
	v_mov_b32_e32 v74, v64
	v_mov_b32_e32 v75, v66
	v_pk_mul_f32 v[76:77], v[76:77], v[76:77]
	s_nop 0
	v_pk_fma_f32 v[74:75], v[74:75], v[74:75], v[76:77]
	v_mov_b32_e32 v77, v72
	v_mov_b32_e32 v76, v74
	v_mov_b32_e32 v72, v75
	v_pk_add_f32 v[72:73], v[76:77], v[72:73]
	ds_bpermute_b32 v75, v88, v73
	ds_bpermute_b32 v74, v88, v72
	s_waitcnt lgkmcnt(0)
	v_pk_add_f32 v[72:73], v[72:73], v[74:75]
	ds_bpermute_b32 v75, v89, v73
	ds_bpermute_b32 v74, v89, v72
	s_waitcnt lgkmcnt(0)
	v_pk_add_f32 v[72:73], v[72:73], v[74:75]
	ds_bpermute_b32 v75, v90, v73
	ds_bpermute_b32 v74, v90, v72
	s_waitcnt lgkmcnt(0)
	v_pk_add_f32 v[72:73], v[72:73], v[74:75]
	ds_bpermute_b32 v75, v91, v73
	ds_bpermute_b32 v74, v91, v72
	s_waitcnt lgkmcnt(0)
	v_pk_add_f32 v[72:73], v[72:73], v[74:75]
	ds_bpermute_b32 v75, v92, v73
	ds_bpermute_b32 v74, v92, v72
	s_waitcnt lgkmcnt(0)
	v_pk_add_f32 v[72:73], v[72:73], v[74:75]
	s_nop 0
	v_pk_add_f32 v[72:73], v[72:73], s[12:13] op_sel_hi:[1,0]
	s_nop 0
	v_mul_f32_e32 v74, 0x4b800000, v73
	v_cmp_gt_f32_e64 s[10:11], s46, v73
	v_cmp_gt_f32_e32 vcc, s46, v72
	s_nop 0
	v_cndmask_b32_e64 v73, v73, v74, s[10:11]
	v_rsq_f32_e32 v73, v73
	s_nop 0
	v_mul_f32_e32 v74, 0x45800000, v73
	v_cndmask_b32_e64 v73, v73, v74, s[10:11]
	v_mul_f32_e32 v74, 0x3db504f3, v73
	v_pk_mul_f32 v[70:71], v[70:71], v[74:75] op_sel_hi:[1,0]
	v_pk_mul_f32 v[68:69], v[68:69], v[74:75] op_sel_hi:[1,0]
	s_nop 0
	v_cvt_pk_bf16_f32 v68, v68, v69
	v_cvt_pk_bf16_f32 v69, v70, v71
	v_mul_f32_e32 v70, 0x4b800000, v72
	v_cndmask_b32_e32 v70, v72, v70, vcc
	v_rsq_f32_e32 v70, v70
	s_nop 0
	v_mul_f32_e32 v71, 0x45800000, v70
	v_cndmask_b32_e32 v70, v70, v71, vcc
	v_mul_f32_e32 v70, 0x3db504f3, v70
	v_pk_mul_f32 v[66:67], v[66:67], v[70:71] op_sel_hi:[1,0]
	v_pk_mul_f32 v[64:65], v[64:65], v[70:71] op_sel_hi:[1,0]
	s_nop 0
	v_cvt_pk_bf16_f32 v64, v64, v65
	v_cvt_pk_bf16_f32 v65, v66, v67
	ds_write2_b64 v96, v[68:69], v[64:65] offset0:68 offset1:102
	v_pk_mul_f32 v[64:65], v[4:5], v[56:57]
	v_pk_mul_f32 v[66:67], v[6:7], v[58:59]
	v_pk_fma_f32 v[60:61], v[0:1], v[60:61], v[64:65]
	v_pk_fma_f32 v[62:63], v[2:3], v[62:63], v[66:67]
	v_pk_fma_f32 v[60:61], v[8:9], v[50:51], v[60:61]
	v_pk_fma_f32 v[62:63], v[10:11], v[52:53], v[62:63]
	v_pk_fma_f32 v[60:61], v[12:13], v[34:35], v[60:61]
	v_pk_fma_f32 v[62:63], v[14:15], v[36:37], v[62:63]
	v_mul_f32_e32 v64, 0xbfb8aa3b, v60
	v_mul_f32_e32 v65, 0xbfb8aa3b, v61
	v_exp_f32_e32 v64, v64
	v_exp_f32_e32 v65, v65
; DI float silu_f(float x) { return x * __builtin_amdgcn_rcpf(1.f + __expf(-x)); }
; DI void dprep_item(LAS unsigned char* ldsh, const Args& a, int l, int item, int tl) {
;     ...
;           for (int j = 0; j < 8; ++j) { f32x4 o = w[0] * xin[j] + w[1] * xin[j + 1] + w[2] * xin[j + 2] + w[3] * xin[j + 3];
;               o[0] = silu_f(o[0]); o[1] = silu_f(o[1]); o[2] = silu_f(o[2]); o[3] = silu_f(o[3]);
;               if (sec < 2) { float ss = (o[0] * o[0] + o[1] * o[1]) + (o[2] * o[2] + o[3] * o[3]);
;                   ss += __shfl_xor(ss, 16); ss += __shfl_xor(ss, 8); ss += __shfl_xor(ss, 4); ss += __shfl_xor(ss, 2); ss += __shfl_xor(ss, 1);
;                   const float sc = rsqrtf(ss + 1e-6f) * (sec == 0 ? 0.08838834764831845f : 1.f); o = o * sc; }
	v_pk_mul_f32 v[68:69], v[6:7], v[52:53]
	v_add_f32_e32 v64, 1.0, v64
	v_add_f32_e32 v65, 1.0, v65
	v_rcp_f32_e32 v64, v64
	v_rcp_f32_e32 v65, v65
	v_pk_fma_f32 v[58:59], v[2:3], v[58:59], v[68:69]
	v_pk_mul_f32 v[60:61], v[60:61], v[64:65]
	v_mul_f32_e32 v64, 0xbfb8aa3b, v62
	v_mul_f32_e32 v65, 0xbfb8aa3b, v63
	v_exp_f32_e32 v64, v64
	v_exp_f32_e32 v65, v65
	v_mov_b32_e32 v66, v61
	v_pk_fma_f32 v[58:59], v[10:11], v[36:37], v[58:59]
	v_add_f32_e32 v64, 1.0, v64
	v_add_f32_e32 v65, 1.0, v65
	v_rcp_f32_e32 v64, v64
	v_rcp_f32_e32 v65, v65
	v_pk_fma_f32 v[58:59], v[14:15], v[42:43], v[58:59]
	v_pk_mul_f32 v[62:63], v[62:63], v[64:65]
	s_nop 0
	v_mov_b32_e32 v67, v63
	v_mov_b32_e32 v64, v60
	v_mov_b32_e32 v65, v62
	v_pk_mul_f32 v[66:67], v[66:67], v[66:67]
	s_nop 0
	v_pk_fma_f32 v[64:65], v[64:65], v[64:65], v[66:67]
	v_pk_mul_f32 v[66:67], v[4:5], v[50:51]
	s_nop 0
	v_pk_fma_f32 v[56:57], v[0:1], v[56:57], v[66:67]
	s_nop 0
	v_pk_fma_f32 v[56:57], v[8:9], v[34:35], v[56:57]
	s_nop 0
	v_pk_fma_f32 v[56:57], v[12:13], v[38:39], v[56:57]
	s_nop 0
	v_mul_f32_e32 v66, 0xbfb8aa3b, v56
	v_mul_f32_e32 v67, 0xbfb8aa3b, v57
	v_exp_f32_e32 v66, v66
	v_exp_f32_e32 v67, v67
	v_add_f32_e32 v66, 1.0, v66
	v_add_f32_e32 v67, 1.0, v67
	v_rcp_f32_e32 v66, v66
	v_rcp_f32_e32 v67, v67
	s_nop 0
	v_pk_mul_f32 v[56:57], v[56:57], v[66:67]
	v_mul_f32_e32 v66, 0xbfb8aa3b, v58
	v_mul_f32_e32 v67, 0xbfb8aa3b, v59
	v_exp_f32_e32 v66, v66
	v_exp_f32_e32 v67, v67
	v_mov_b32_e32 v68, v57
	v_add_f32_e32 v66, 1.0, v66
	v_add_f32_e32 v67, 1.0, v67
	v_rcp_f32_e32 v66, v66
	v_rcp_f32_e32 v67, v67
	s_nop 0
	v_pk_mul_f32 v[58:59], v[58:59], v[66:67]
	s_nop 0
	v_mov_b32_e32 v69, v59
	v_mov_b32_e32 v66, v56
	v_mov_b32_e32 v67, v58
	v_pk_mul_f32 v[68:69], v[68:69], v[68:69]
	s_nop 0
	v_pk_fma_f32 v[66:67], v[66:67], v[66:67], v[68:69]
	v_mov_b32_e32 v69, v64
	v_mov_b32_e32 v68, v66
	v_mov_b32_e32 v64, v67
	v_pk_add_f32 v[64:65], v[68:69], v[64:65]
	ds_bpermute_b32 v67, v88, v65
	ds_bpermute_b32 v66, v88, v64
	s_waitcnt lgkmcnt(0)
	v_pk_add_f32 v[64:65], v[64:65], v[66:67]
	ds_bpermute_b32 v67, v89, v65
	ds_bpermute_b32 v66, v89, v64
	s_waitcnt lgkmcnt(0)
	v_pk_add_f32 v[64:65], v[64:65], v[66:67]
	ds_bpermute_b32 v67, v90, v65
	ds_bpermute_b32 v66, v90, v64
	s_waitcnt lgkmcnt(0)
	v_pk_add_f32 v[64:65], v[64:65], v[66:67]
	ds_bpermute_b32 v67, v91, v65
	ds_bpermute_b32 v66, v91, v64
	s_waitcnt lgkmcnt(0)
	v_pk_add_f32 v[64:65], v[64:65], v[66:67]
	ds_bpermute_b32 v67, v92, v65
	ds_bpermute_b32 v66, v92, v64
	s_waitcnt lgkmcnt(0)
; #define LAS __attribute__((address_space(3)))
; DI unsigned pk2(float a, float b) { f32x2 v = {a, b}; nbf2 r = __builtin_convertvector(v, nbf2); return __builtin_bit_cast(unsigned, r); }
; DI float silu_f(float x) { return x * __builtin_amdgcn_rcpf(1.f + __expf(-x)); }
; DI void dprep_item(LAS unsigned char* ldsh, const Args& a, int l, int item, int tl) {
;     ...
;           for (int j = 0; j < 8; ++j) { f32x4 o = w[0] * xin[j] + w[1] * xin[j + 1] + w[2] * xin[j + 2] + w[3] * xin[j + 3];
;               o[0] = silu_f(o[0]); o[1] = silu_f(o[1]); o[2] = silu_f(o[2]); o[3] = silu_f(o[3]);
;               if (sec < 2) { float ss = (o[0] * o[0] + o[1] * o[1]) + (o[2] * o[2] + o[3] * o[3]);
;                   ss += __shfl_xor(ss, 16); ss += __shfl_xor(ss, 8); ss += __shfl_xor(ss, 4); ss += __shfl_xor(ss, 2); ss += __shfl_xor(ss, 1);
;                   const float sc = rsqrtf(ss + 1e-6f) * (sec == 0 ? 0.08838834764831845f : 1.f); o = o * sc; }
;               u32x2 pw; pw.x = pk2(o[0], o[1]); pw.y = pk2(o[2], o[3]); *(LAS u32x2*)(dst + (rg * 8 + j) * 136 + c0) = pw; }
	v_pk_add_f32 v[64:65], v[64:65], v[66:67]
	s_nop 0
	v_pk_add_f32 v[64:65], v[64:65], s[12:13] op_sel_hi:[1,0]
	s_nop 0
	v_mul_f32_e32 v66, 0x4b800000, v65
	v_cmp_gt_f32_e64 s[10:11], s46, v65
	v_cmp_gt_f32_e32 vcc, s46, v64
	s_nop 0
	v_cndmask_b32_e64 v65, v65, v66, s[10:11]
	v_rsq_f32_e32 v65, v65
	s_nop 0
	v_mul_f32_e32 v66, 0x45800000, v65
	v_cndmask_b32_e64 v65, v65, v66, s[10:11]
	v_mul_f32_e32 v66, 0x3db504f3, v65
	v_pk_mul_f32 v[62:63], v[62:63], v[66:67] op_sel_hi:[1,0]
	v_pk_mul_f32 v[60:61], v[60:61], v[66:67] op_sel_hi:[1,0]
	s_nop 0
	v_cvt_pk_bf16_f32 v60, v60, v61
	v_cvt_pk_bf16_f32 v61, v62, v63
	v_mul_f32_e32 v62, 0x4b800000, v64
	v_cndmask_b32_e32 v62, v64, v62, vcc
	v_rsq_f32_e32 v62, v62
	s_nop 0
	v_mul_f32_e32 v63, 0x45800000, v62
	v_cndmask_b32_e32 v62, v62, v63, vcc
	v_mul_f32_e32 v62, 0x3db504f3, v62
	v_pk_mul_f32 v[58:59], v[58:59], v[62:63] op_sel_hi:[1,0]
	v_pk_mul_f32 v[56:57], v[56:57], v[62:63] op_sel_hi:[1,0]
	s_nop 0
	v_cvt_pk_bf16_f32 v56, v56, v57
	v_cvt_pk_bf16_f32 v57, v58, v59
	ds_write2_b64 v96, v[60:61], v[56:57] offset0:136 offset1:170
	v_pk_mul_f32 v[56:57], v[4:5], v[34:35]
	v_pk_mul_f32 v[4:5], v[4:5], v[38:39]
	v_pk_fma_f32 v[50:51], v[0:1], v[50:51], v[56:57]
	v_pk_fma_f32 v[0:1], v[0:1], v[34:35], v[4:5]
	v_pk_fma_f32 v[50:51], v[8:9], v[38:39], v[50:51]
	v_pk_fma_f32 v[0:1], v[8:9], v[44:45], v[0:1]
	v_pk_fma_f32 v[50:51], v[12:13], v[44:45], v[50:51]
	v_pk_fma_f32 v[0:1], v[12:13], v[48:49], v[0:1]
	v_mul_f32_e32 v56, 0xbfb8aa3b, v50
	v_mul_f32_e32 v57, 0xbfb8aa3b, v51
	v_mul_f32_e32 v4, 0xbfb8aa3b, v0
	v_mul_f32_e32 v5, 0xbfb8aa3b, v1
	v_exp_f32_e32 v56, v56
	v_exp_f32_e32 v57, v57
	v_exp_f32_e32 v4, v4
	v_exp_f32_e32 v5, v5
	v_add_f32_e32 v56, 1.0, v56
	v_add_f32_e32 v57, 1.0, v57
	v_add_f32_e32 v4, 1.0, v4
	v_add_f32_e32 v5, 1.0, v5
	v_pk_mul_f32 v[58:59], v[6:7], v[36:37]
	v_rcp_f32_e32 v56, v56
	v_rcp_f32_e32 v57, v57
	v_pk_mul_f32 v[6:7], v[6:7], v[42:43]
	v_rcp_f32_e32 v4, v4
	v_rcp_f32_e32 v5, v5
	v_pk_fma_f32 v[52:53], v[2:3], v[52:53], v[58:59]
	v_pk_fma_f32 v[2:3], v[2:3], v[36:37], v[6:7]
	v_pk_fma_f32 v[52:53], v[10:11], v[42:43], v[52:53]
	v_pk_fma_f32 v[2:3], v[10:11], v[46:47], v[2:3]
	v_pk_fma_f32 v[52:53], v[14:15], v[46:47], v[52:53]
	v_pk_fma_f32 v[2:3], v[14:15], v[54:55], v[2:3]
	v_pk_mul_f32 v[50:51], v[50:51], v[56:57]
	v_mul_f32_e32 v56, 0xbfb8aa3b, v52
	v_mul_f32_e32 v57, 0xbfb8aa3b, v53
	v_pk_mul_f32 v[0:1], v[0:1], v[4:5]
	v_mul_f32_e32 v4, 0xbfb8aa3b, v2
	v_mul_f32_e32 v5, 0xbfb8aa3b, v3
	v_exp_f32_e32 v56, v56
	v_exp_f32_e32 v57, v57
	v_exp_f32_e32 v4, v4
	v_exp_f32_e32 v5, v5
	v_add_f32_e32 v56, 1.0, v56
	v_add_f32_e32 v57, 1.0, v57
	v_add_f32_e32 v4, 1.0, v4
	v_add_f32_e32 v5, 1.0, v5
	v_rcp_f32_e32 v56, v56
	v_rcp_f32_e32 v57, v57
	v_rcp_f32_e32 v4, v4
	v_rcp_f32_e32 v5, v5
	v_mov_b32_e32 v58, v51
	v_pk_mul_f32 v[52:53], v[52:53], v[56:57]
	v_mov_b32_e32 v6, v1
	v_pk_mul_f32 v[2:3], v[2:3], v[4:5]
	v_mov_b32_e32 v59, v53
	v_mov_b32_e32 v7, v3
	v_mov_b32_e32 v56, v50
	v_mov_b32_e32 v57, v52
	v_pk_mul_f32 v[58:59], v[58:59], v[58:59]
	v_mov_b32_e32 v4, v0
	v_mov_b32_e32 v5, v2
	v_pk_mul_f32 v[6:7], v[6:7], v[6:7]
	v_pk_fma_f32 v[56:57], v[56:57], v[56:57], v[58:59]
	v_pk_fma_f32 v[4:5], v[4:5], v[4:5], v[6:7]
	v_mov_b32_e32 v7, v56
	v_mov_b32_e32 v6, v4
	v_mov_b32_e32 v56, v5
	v_pk_add_f32 v[4:5], v[6:7], v[56:57]
	ds_bpermute_b32 v7, v88, v5
	ds_bpermute_b32 v6, v88, v4
	s_waitcnt lgkmcnt(0)
	v_pk_add_f32 v[4:5], v[4:5], v[6:7]
	ds_bpermute_b32 v7, v89, v5
	ds_bpermute_b32 v6, v89, v4
	s_waitcnt lgkmcnt(0)
	v_pk_add_f32 v[4:5], v[4:5], v[6:7]
	ds_bpermute_b32 v7, v90, v5
	ds_bpermute_b32 v6, v90, v4
	s_waitcnt lgkmcnt(0)
	v_pk_add_f32 v[4:5], v[4:5], v[6:7]
	ds_bpermute_b32 v7, v91, v5
	ds_bpermute_b32 v6, v91, v4
	s_waitcnt lgkmcnt(0)
	v_pk_add_f32 v[4:5], v[4:5], v[6:7]
	ds_bpermute_b32 v7, v92, v5
	ds_bpermute_b32 v6, v92, v4
	s_waitcnt lgkmcnt(0)
	v_pk_add_f32 v[4:5], v[4:5], v[6:7]
	s_nop 0
	v_pk_add_f32 v[4:5], v[4:5], s[12:13] op_sel_hi:[1,0]
	s_mov_b64 s[12:13], 0
	v_mul_f32_e32 v6, 0x4b800000, v5
	v_cmp_gt_f32_e64 s[10:11], s46, v5
	v_cmp_gt_f32_e32 vcc, s46, v4
	s_nop 0
	v_cndmask_b32_e64 v5, v5, v6, s[10:11]
	v_rsq_f32_e32 v5, v5
	s_nop 0
	v_mul_f32_e32 v6, 0x45800000, v5
	v_cndmask_b32_e64 v5, v5, v6, s[10:11]
	v_mul_f32_e32 v6, 0x3db504f3, v5
	v_mul_f32_e32 v5, 0x4b800000, v4
	v_cndmask_b32_e32 v4, v4, v5, vcc
	v_rsq_f32_e32 v4, v4
	v_pk_mul_f32 v[8:9], v[52:53], v[6:7] op_sel_hi:[1,0]
	v_pk_mul_f32 v[6:7], v[50:51], v[6:7] op_sel_hi:[1,0]
	v_mad_i64_i32 v[34:35], s[10:11], v94, s42, 0
	v_mul_f32_e32 v5, 0x45800000, v4
	v_cndmask_b32_e32 v4, v4, v5, vcc
	v_mul_f32_e32 v4, 0x3db504f3, v4
	v_pk_mul_f32 v[2:3], v[2:3], v[4:5] op_sel_hi:[1,0]
	v_pk_mul_f32 v[0:1], v[0:1], v[4:5] op_sel_hi:[1,0]
	v_cvt_pk_bf16_f32 v6, v6, v7
	v_cvt_pk_bf16_f32 v0, v0, v1
	v_cvt_pk_bf16_f32 v1, v2, v3
	v_or_b32_e32 v2, 7, v81
	v_cvt_pk_bf16_f32 v7, v8, v9
	v_mul_u32_u24_e32 v72, 0x110, v2
	v_mad_u32_u24 v2, v2, s47, v86
	v_mad_i64_i32 v[36:37], s[10:11], v95, s42, 0
	ds_write_b64 v96, v[6:7] offset:1632
	ds_write_b64 v2, v[0:1]
	s_branch .LBB0_231

; DI const float* INP(const Args& a, int i) { asm volatile("" : "+s"(i)); return a.in[i]; }
; DI float bflo(unsigned w) { return __uint_as_float(w << 16); }
; DI float bfhi(unsigned w) { return __uint_as_float(w & 0xffff0000u); }
; DI void dprep_item(LAS unsigned char* ldsh, const Args& a, int l, int item, int tl) {
;     ...
;     { const int cg4 = tl & 31, rg = tl >> 5, c0 = cg4 * 4;
;       for (int sec = 0; sec < 3; ++sec) {
;           const int col = sec * 512 + h * 128 + c0;
;           f32x4 w[4];
; #pragma unroll
;           for (int i = 0; i < 4; ++i) w[i] = *(const f32x4*)(INP(a, 11) + (size_t)(l * 4 + i) * QKVD + col);
;           f32x4 xin[11];
; #pragma unroll
;           for (int i = 0; i < 11; ++i) { const int tpos = n * 64 + rg * 8 - 3 + i;
;               if (tpos >= 0) { const u32x2 raw = *(const u32x2*)(PROJ + (size_t)(r0 + rg * 8 - 3 + i) * NPROJ + col); xin[i] = (f32x4){bflo(raw.x), bfhi(raw.x), bflo(raw.y), bfhi(raw.y)}; }
;               else xin[i] = (f32x4){0.f, 0.f, 0.f, 0.f}; }
.LBB0_231:
	s_mov_b32 s10, 11
	s_ashr_i32 s11, s10, 31
	s_lshl_b64 s[10:11], s[10:11], 3
	s_add_u32 s10, s0, s10
	s_addc_u32 s11, s1, s11
	s_load_dwordx2 s[10:11], s[10:11], 0x0
	v_or_b32_e32 v128, s38, v84
	v_lshlrev_b64 v[12:13], 2, v[128:129]
	v_lshl_add_u64 v[38:39], v[128:129], 1, s[72:73]
	v_mov_b32_e32 v50, 0
	s_waitcnt lgkmcnt(0)
	s_add_u32 s10, s10, s2
	s_addc_u32 s11, s11, s14
	v_lshl_add_u64 v[0:1], s[10:11], 0, v[12:13]
	s_mov_b32 s10, 11
	global_load_dwordx4 v[0:3], v[0:1], off
	s_ashr_i32 s11, s10, 31
	s_lshl_b64 s[10:11], s[10:11], 3
	s_add_u32 s10, s0, s10
	s_addc_u32 s11, s1, s11
	s_load_dwordx2 s[10:11], s[10:11], 0x0
	v_mov_b32_e32 v54, 0
	v_mov_b32_e32 v55, 0
	v_mov_b32_e32 v62, 0
	v_mov_b32_e32 v63, 0
	s_waitcnt lgkmcnt(0)
	s_add_u32 s10, s10, s16
	s_addc_u32 s11, s11, s15
	v_lshl_add_u64 v[4:5], s[10:11], 0, v[12:13]
	s_mov_b32 s10, 11
	global_load_dwordx4 v[4:7], v[4:5], off
	s_ashr_i32 s11, s10, 31
	s_lshl_b64 s[10:11], s[10:11], 3
	s_add_u32 s10, s0, s10
	s_addc_u32 s11, s1, s11
	s_load_dwordx2 s[10:11], s[10:11], 0x0
	s_waitcnt lgkmcnt(0)
	s_add_u32 s10, s10, s28
	s_addc_u32 s11, s11, s17
	v_lshl_add_u64 v[8:9], s[10:11], 0, v[12:13]
	s_mov_b32 s10, 11
	global_load_dwordx4 v[8:11], v[8:9], off
	s_ashr_i32 s11, s10, 31
	s_lshl_b64 s[10:11], s[10:11], 3
	s_add_u32 s10, s0, s10
	s_addc_u32 s11, s1, s11
	s_load_dwordx2 s[10:11], s[10:11], 0x0
	s_waitcnt lgkmcnt(0)
	s_add_u32 s10, s10, s34
	s_addc_u32 s11, s11, s29
	v_lshl_add_u64 v[12:13], s[10:11], 0, v[12:13]
	global_load_dwordx4 v[12:15], v[12:13], off
	v_mov_b32_e32 v180, 0
	v_mov_b32_e32 v181, 0
	s_and_saveexec_b64 s[10:11], s[8:9]
	s_cbranch_execz .LBB0_233
	v_lshl_add_u64 v[42:43], v[38:39], 0, v[34:35]
	global_load_dwordx2 v[180:181], v[42:43], off
.LBB0_233:
	s_or_b64 exec, exec, s[10:11]
	v_mov_b32_e32 v51, 0
	v_mov_b32_e32 v66, 0
	v_mov_b32_e32 v67, 0
	v_mov_b32_e32 v182, 0
	v_mov_b32_e32 v183, 0
	s_and_saveexec_b64 s[10:11], s[8:9]
	s_cbranch_execz .LBB0_235
	v_lshl_add_u64 v[42:43], v[38:39], 0, v[36:37]
	global_load_dwordx2 v[182:183], v[42:43], off
.LBB0_235:
	s_or_b64 exec, exec, s[10:11]
	v_mov_b32_e32 v56, 0
	v_mov_b32_e32 v57, v56
	v_mov_b32_e32 v60, v56
	v_mov_b32_e32 v61, v56
	v_mov_b32_e32 v184, 0
	v_mov_b32_e32 v185, 0
	s_and_saveexec_b64 s[10:11], s[8:9]
	s_cbranch_execz .LBB0_237
	v_lshl_add_u64 v[42:43], v[38:39], 0, v[16:17]
	global_load_dwordx2 v[184:185], v[42:43], off
.LBB0_237:
	s_or_b64 exec, exec, s[10:11]
	s_waitcnt vmcnt(0)
	v_lshlrev_b32_e32 v54, 16, v180
	v_and_b32_e32 v55, 0xffff0000, v180
	v_lshlrev_b32_e32 v62, 16, v181
	v_and_b32_e32 v63, 0xffff0000, v181
	v_lshlrev_b32_e32 v50, 16, v182
	v_and_b32_e32 v51, 0xffff0000, v182
	v_lshlrev_b32_e32 v66, 16, v183
	v_and_b32_e32 v67, 0xffff0000, v183
	v_lshlrev_b32_e32 v56, 16, v184
	v_and_b32_e32 v57, 0xffff0000, v184
	v_lshlrev_b32_e32 v60, 16, v185
	v_and_b32_e32 v61, 0xffff0000, v185
	v_lshl_add_u64 v[42:43], v[38:39], 0, v[18:19]
	global_load_dwordx2 v[64:65], v[42:43], off
	v_lshl_add_u64 v[42:43], v[38:39], 0, v[20:21]
	v_lshl_add_u64 v[44:45], v[38:39], 0, v[22:23]
	v_lshl_add_u64 v[46:47], v[38:39], 0, v[24:25]
	v_lshl_add_u64 v[68:69], v[38:39], 0, v[26:27]
	v_lshl_add_u64 v[70:71], v[38:39], 0, v[28:29]
	v_lshl_add_u64 v[74:75], v[38:39], 0, v[30:31]
	v_lshl_add_u64 v[38:39], v[38:39], 0, v[32:33]
	global_load_dwordx2 v[58:59], v[42:43], off
	global_load_dwordx2 v[52:53], v[44:45], off
	global_load_dwordx2 v[48:49], v[46:47], off
	s_nop 0
	global_load_dwordx2 v[46:47], v[68:69], off
	global_load_dwordx2 v[44:45], v[70:71], off
	global_load_dwordx2 v[42:43], v[74:75], off
	s_nop 0
	global_load_dwordx2 v[38:39], v[38:39], off
	s_waitcnt vmcnt(10)
	v_pk_mul_f32 v[68:69], v[6:7], v[66:67]
	v_pk_mul_f32 v[70:71], v[4:5], v[50:51]
	v_pk_fma_f32 v[62:63], v[2:3], v[62:63], v[68:69]
	v_pk_fma_f32 v[54:55], v[0:1], v[54:55], v[70:71]
	s_xor_b64 s[12:13], s[12:13], -1
	s_waitcnt vmcnt(9)
	v_pk_fma_f32 v[54:55], v[8:9], v[56:57], v[54:55]
	v_pk_fma_f32 v[68:69], v[10:11], v[60:61], v[62:63]
	v_cndmask_b32_e64 v73, 0, 1, s[12:13]
	v_cmp_ne_u32_e64 s[10:11], 1, v73
	s_andn2_b64 vcc, exec, s[12:13]
	s_waitcnt vmcnt(7)
	v_lshlrev_b32_e32 v62, 16, v64
	v_and_b32_e32 v63, 0xffff0000, v64
	v_lshlrev_b32_e32 v64, 16, v65
	v_and_b32_e32 v65, 0xffff0000, v65
	v_pk_fma_f32 v[70:71], v[14:15], v[64:65], v[68:69]
	v_pk_fma_f32 v[54:55], v[12:13], v[62:63], v[54:55]
	v_mul_f32_e32 v74, 0xbfb8aa3b, v70
	v_mul_f32_e32 v69, 0xbfb8aa3b, v54
	v_mul_f32_e32 v73, 0xbfb8aa3b, v55
	v_mul_f32_e32 v75, 0xbfb8aa3b, v71
	v_mov_b32_e32 v68, v54
	v_exp_f32_e32 v54, v69
	v_exp_f32_e32 v69, v73
	v_exp_f32_e32 v73, v74
	v_exp_f32_e32 v74, v75
	v_add_f32_e32 v54, 1.0, v54
	v_add_f32_e32 v69, 1.0, v69
	v_add_f32_e32 v73, 1.0, v73
	v_add_f32_e32 v77, 1.0, v74
	v_rcp_f32_e32 v74, v54
	v_rcp_f32_e32 v76, v69
	v_rcp_f32_e32 v75, v73
	v_rcp_f32_e32 v77, v77
	v_mov_b32_e32 v69, v70
	v_mov_b32_e32 v70, v55
	v_pk_mul_f32 v[68:69], v[68:69], v[74:75]
	v_pk_mul_f32 v[70:71], v[70:71], v[76:77]
	s_cbranch_vccnz .LBB0_239
	v_pk_mul_f32 v[54:55], v[70:71], v[70:71]
	s_nop 0
	v_pk_fma_f32 v[54:55], v[68:69], v[68:69], v[54:55]
	s_nop 0
	v_add_f32_e32 v54, v54, v55
	ds_bpermute_b32 v55, v88, v54
	s_waitcnt lgkmcnt(0)
	v_add_f32_e32 v54, v54, v55
	ds_bpermute_b32 v55, v89, v54
	s_waitcnt lgkmcnt(0)
	v_add_f32_e32 v54, v54, v55
	ds_bpermute_b32 v55, v90, v54
	s_waitcnt lgkmcnt(0)
	v_add_f32_e32 v54, v54, v55
	ds_bpermute_b32 v55, v91, v54
	s_waitcnt lgkmcnt(0)
	v_add_f32_e32 v54, v54, v55
	ds_bpermute_b32 v55, v92, v54
	s_waitcnt lgkmcnt(0)
	v_add_f32_e32 v54, v54, v55
	v_add_f32_e32 v54, 0x358637bd, v54
	v_mul_f32_e32 v55, 0x4b800000, v54
	v_cmp_gt_f32_e32 vcc, s46, v54
	s_nop 1
	v_cndmask_b32_e32 v54, v54, v55, vcc
	v_rsq_f32_e32 v73, v54
	v_mov_b32_e32 v54, v68
	v_mov_b32_e32 v55, v70
	v_mov_b32_e32 v70, v69
	v_mul_f32_e32 v68, 0x45800000, v73
	v_cndmask_b32_e32 v68, v73, v68, vcc
	v_pk_mul_f32 v[74:75], v[70:71], v[68:69] op_sel_hi:[1,0]
	v_pk_mul_f32 v[68:69], v[54:55], v[68:69] op_sel_hi:[1,0]
	v_mov_b32_e32 v71, v75
	v_mov_b32_e32 v70, v69
	v_mov_b32_e32 v69, v74
